# v18 + phase0 (weight convert/transpose) rewritten: flat tile stream over all matrices, tiles via LDS-DMA into a 7-slot LDS ring with 5 tiles in flight, one barrier per tile
# baseline (speedup 1.0000x reference)
; __device__ __forceinline__ int tid_v() { int t = threadIdx.x; asm volatile("" : "+v"(t)); return t; }
; __device__ __forceinline__ int bid_s() { int b = blockIdx.x; asm volatile("" : "+s"(b)); return b; }
; #define WSP() ((unsigned char*)karg_ptr<35 * 8>())
; __device__ __forceinline__ void tconv(const float* __restrict__ src, bf16_t* __restrict__ dst, int K, int N, const float* __restrict__ scale, float* tile, int& rot) {
;     const int tk = K >> 6, tn = N >> 6, nt = tk * tn, G = gridDim.x;
;     const int tid = tid_v(), lr = tid >> 4, lc = (tid & 15) * 4;
;     const int sn = tid >> 3, sk = (tid & 7) * 8;
;     int t = (int)((bid_s() + G - (rot % G)) % G);
;     f32x4 v0, v1;
;     if (t < nt) { const int kt = t / tn, k0 = kt << 6, n0 = (t - kt * tn) << 6; v0 = *(const f32x4*)(src + (size_t)(k0 + lr) * N + n0 + lc); v1 = *(const f32x4*)(src + (size_t)(k0 + lr + 32) * N + n0 + lc); }
; __device__ __forceinline__ void phase0(unsigned char* shm) {
;     ...
;     for (int l = 0; l < 2; ++l) {
;         bf16_t* W = (bf16_t*)(WSP() + (size_t)l * WL_BYTES);
;         tconv(IN(3) + (size_t)l * 1024 * 8960, W + oWin, 1024, 8960, IN(2) + l * 1024, tile, rot);
;         for (int k = 0; k < 4; ++k) tconv(IN(23) + (size_t)(l * 4 + k) * 512 * 1024, W + oWb + (size_t)k * 1024 * 512, 512, 1024, nullptr, tile, rot);
;         tconv(IN(24) + (size_t)l * 1024 * 1024, W + oWo, 1024, 1024, nullptr, tile, rot);
;         tconv(IN(26) + (size_t)l * 1024 * 5632, W + oWup, 1024, 5632, IN(25) + l * 1024, tile, rot);
;         tconv(IN(29) + (size_t)l * 2816 * 1024, W + oWd, 2816, 1024, nullptr, tile, rot);
;         tconv(IN(31) + (size_t)l * 256 * 1024, W + oWp, 256, 1024, nullptr, tile, rot);
;         tconv(IN(32) + (size_t)l * 1024 * 1024, W + oWg, 1024, 1024, IN(30) + l * 1024, tile, rot);
;         for (int g = 0; g < 4; ++g) tconv(IN(4) + (size_t)(l * 4 + g) * 128 * 128, W + oPw + (size_t)g * 16384, 128, 128, nullptr, tile, rot);
;         tconv(IN(8) + (size_t)l * 64 * 512, W + oW2, 64, 512, nullptr, tile, rot);
;         tconv(IN(10) + (size_t)l * 64 * 512, W + oA2, 64, 512, nullptr, tile, rot);
;         tconv(IN(11) + (size_t)l * 128 * 512, W + oG2, 128, 512, nullptr, tile, rot);
;     }
.LBB0_7:
	s_load_dwordx2 s[36:37], s[0:1], 0x18
	s_load_dwordx2 s[38:39], s[0:1], 0x10
	s_load_dwordx2 s[40:41], s[0:1], 0xb8
	s_load_dwordx2 s[42:43], s[0:1], 0xc0
	s_load_dwordx2 s[44:45], s[0:1], 0xd0
	s_load_dwordx2 s[46:47], s[0:1], 0xc8
	s_load_dwordx2 s[48:49], s[0:1], 0xe8
	s_load_dwordx2 s[50:51], s[0:1], 0xf8
	s_load_dwordx2 s[52:53], s[0:1], 0x100
	s_load_dwordx2 s[54:55], s[0:1], 0xf0
	s_load_dwordx2 s[56:57], s[0:1], 0x20
	s_load_dwordx2 s[58:59], s[0:1], 0x40
	s_load_dwordx2 s[60:61], s[0:1], 0x50
	s_load_dwordx2 s[62:63], s[0:1], 0x58
	s_waitcnt lgkmcnt(0)
	v_lshrrev_b32_e32 v34, 6, v179
	v_and_b32_e32 v35, 63, v179
	v_lshrrev_b32_e32 v36, 4, v35
	v_lshl_add_u32 v1, v34, 3, v36
	v_add_u32_e32 v2, 4, v1
	v_and_b32_e32 v3, 15, v35
	v_lshlrev_b32_e32 v3, 4, v3
	v_lshlrev_b32_e32 v11, 4, v35
	v_lshrrev_b32_e32 v6, 3, v179
	v_and_b32_e32 v37, 7, v179
	v_lshlrev_b32_e32 v7, 4, v37
	v_mul_u32_u24_e32 v9, 0x820, v37
	v_lshl_add_u32 v9, v6, 2, v9
	v_lshlrev_b32_e32 v10, 5, v37
	s_nop 0
	v_readfirstlane_b32 s67, v34
	s_mul_i32 s67, s67, 0x820
	s_mov_b32 s64, s87
	s_mov_b32 s65, 0
	s_mov_b32 s66, 0
	s_mov_b32 s68, 0
.Lp0_pro:
	s_lshl_b32 s69, s68, 8
	s_add_u32 s69, s69, s87
	s_cmp_lt_u32 s69, 10976
	s_cselect_b32 s69, s69, s87
	s_cmp_ge_u32 s69, 5488
	s_cselect_b32 s2, 1, 0
	s_mul_i32 s3, s2, 5488
	s_sub_u32 s3, s69, s3
	s_cmp_lt_u32 s3, 2240
	s_cbranch_scc1 .Lp0p_m0
	s_cmp_lt_u32 s3, 2368
	s_cbranch_scc1 .Lp0p_m1
	s_cmp_lt_u32 s3, 2496
	s_cbranch_scc1 .Lp0p_m2
	s_cmp_lt_u32 s3, 2624
	s_cbranch_scc1 .Lp0p_m3
	s_cmp_lt_u32 s3, 2752
	s_cbranch_scc1 .Lp0p_m4
	s_cmp_lt_u32 s3, 3008
	s_cbranch_scc1 .Lp0p_m5
	s_cmp_lt_u32 s3, 4416
	s_cbranch_scc1 .Lp0p_m6
	s_cmp_lt_u32 s3, 5120
	s_cbranch_scc1 .Lp0p_m7
	s_cmp_lt_u32 s3, 5184
	s_cbranch_scc1 .Lp0p_m8
	s_cmp_lt_u32 s3, 5440
	s_cbranch_scc1 .Lp0p_m9
	s_cmp_lt_u32 s3, 5444
	s_cbranch_scc1 .Lp0p_m10
	s_cmp_lt_u32 s3, 5448
	s_cbranch_scc1 .Lp0p_m11
	s_cmp_lt_u32 s3, 5452
	s_cbranch_scc1 .Lp0p_m12
	s_cmp_lt_u32 s3, 5456
	s_cbranch_scc1 .Lp0p_m13
	s_cmp_lt_u32 s3, 5464
	s_cbranch_scc1 .Lp0p_m14
	s_cmp_lt_u32 s3, 5472
	s_cbranch_scc1 .Lp0p_m15
	s_sub_u32 s4, s3, 5472
	s_mul_hi_u32 s5, s4, 0x20000000
	s_mul_i32 s8, s5, 8
	s_sub_u32 s8, s4, s8
	s_mul_i32 s9, s5, 0x20000
	s_lshl_b32 s10, s8, 8
	s_add_u32 s9, s9, s10
	s_mul_i32 s10, s2, 0x40000
	s_add_u32 s9, s9, s10
	s_add_u32 s18, s62, s9
	s_addc_u32 s19, s63, 0
	s_mov_b32 s20, 0x800
	s_mov_b64 s[22:23], s[38:39]
	s_branch .Lp0p_j
.Lp0p_m0:
	s_sub_u32 s4, s3, 0
	s_mul_hi_u32 s5, s4, 0x1d41d42
	s_mul_i32 s8, s5, 140
	s_sub_u32 s8, s4, s8
	s_mul_i32 s9, s5, 0x230000
	s_lshl_b32 s10, s8, 8
	s_add_u32 s9, s9, s10
	s_mul_i32 s10, s2, 0x2300000
	s_add_u32 s9, s9, s10
	s_add_u32 s18, s36, s9
	s_addc_u32 s19, s37, 0
	s_mov_b32 s20, 0x8c00
	s_lshl_b32 s9, s2, 12
	s_lshl_b32 s10, s5, 8
	s_add_u32 s9, s9, s10
	s_add_u32 s22, s38, s9
	s_addc_u32 s23, s39, 0
	s_branch .Lp0p_j
.Lp0p_m1:
	s_sub_u32 s4, s3, 2240
	s_mul_hi_u32 s5, s4, 0x10000000
	s_mul_i32 s8, s5, 16
	s_sub_u32 s8, s4, s8
	s_mul_i32 s9, s5, 0x40000
	s_lshl_b32 s10, s8, 8
	s_add_u32 s9, s9, s10
	s_mul_i32 s10, s2, 0x800000
	s_add_u32 s9, s9, s10
	s_add_u32 s18, s40, s9
	s_addc_u32 s19, s41, 0
	s_mov_b32 s20, 0x1000
	s_mov_b64 s[22:23], s[38:39]
	s_branch .Lp0p_j
.Lp0p_m2:
	s_sub_u32 s4, s3, 2368
	s_mul_hi_u32 s5, s4, 0x10000000
	s_mul_i32 s8, s5, 16
	s_sub_u32 s8, s4, s8
	s_mul_i32 s9, s5, 0x40000
	s_lshl_b32 s10, s8, 8
	s_add_u32 s9, s9, s10
	s_mul_i32 s10, s2, 0x800000
	s_add_u32 s9, s9, s10
	s_add_u32 s9, s9, 0x200000
	s_add_u32 s18, s40, s9
	s_addc_u32 s19, s41, 0
	s_mov_b32 s20, 0x1000
	s_mov_b64 s[22:23], s[38:39]
	s_branch .Lp0p_j
.Lp0p_m3:
	s_sub_u32 s4, s3, 2496
	s_mul_hi_u32 s5, s4, 0x10000000
	s_mul_i32 s8, s5, 16
	s_sub_u32 s8, s4, s8
	s_mul_i32 s9, s5, 0x40000
	s_lshl_b32 s10, s8, 8
	s_add_u32 s9, s9, s10
	s_mul_i32 s10, s2, 0x800000
	s_add_u32 s9, s9, s10
	s_add_u32 s9, s9, 0x400000
	s_add_u32 s18, s40, s9
	s_addc_u32 s19, s41, 0
	s_mov_b32 s20, 0x1000
	s_mov_b64 s[22:23], s[38:39]
	s_branch .Lp0p_j
.Lp0p_m4:
	s_sub_u32 s4, s3, 2624
	s_mul_hi_u32 s5, s4, 0x10000000
	s_mul_i32 s8, s5, 16
	s_sub_u32 s8, s4, s8
	s_mul_i32 s9, s5, 0x40000
	s_lshl_b32 s10, s8, 8
	s_add_u32 s9, s9, s10
	s_mul_i32 s10, s2, 0x800000
	s_add_u32 s9, s9, s10
	s_add_u32 s9, s9, 0x600000
	s_add_u32 s18, s40, s9
	s_addc_u32 s19, s41, 0
	s_mov_b32 s20, 0x1000
	s_mov_b64 s[22:23], s[38:39]
	s_branch .Lp0p_j
.Lp0p_m5:
	s_sub_u32 s4, s3, 2752
	s_mul_hi_u32 s5, s4, 0x10000000
	s_mul_i32 s8, s5, 16
	s_sub_u32 s8, s4, s8
	s_mul_i32 s9, s5, 0x40000
	s_lshl_b32 s10, s8, 8
	s_add_u32 s9, s9, s10
	s_mul_i32 s10, s2, 0x400000
	s_add_u32 s9, s9, s10
	s_add_u32 s18, s42, s9
	s_addc_u32 s19, s43, 0
	s_mov_b32 s20, 0x1000
	s_mov_b64 s[22:23], s[38:39]
	s_branch .Lp0p_j
.Lp0p_m6:
	s_sub_u32 s4, s3, 3008
	s_mul_hi_u32 s5, s4, 0x2e8ba2f
	s_mul_i32 s8, s5, 88
	s_sub_u32 s8, s4, s8
	s_mul_i32 s9, s5, 0x160000
	s_lshl_b32 s10, s8, 8
	s_add_u32 s9, s9, s10
	s_mul_i32 s10, s2, 0x1600000
	s_add_u32 s9, s9, s10
	s_add_u32 s18, s44, s9
	s_addc_u32 s19, s45, 0
	s_mov_b32 s20, 0x5800
	s_lshl_b32 s9, s2, 12
	s_lshl_b32 s10, s5, 8
	s_add_u32 s9, s9, s10
	s_add_u32 s22, s46, s9
	s_addc_u32 s23, s47, 0
	s_branch .Lp0p_j
; #define WSP() ((unsigned char*)karg_ptr<35 * 8>())
; __device__ __forceinline__ void tconv(const float* __restrict__ src, bf16_t* __restrict__ dst, int K, int N, const float* __restrict__ scale, float* tile, int& rot) {
;     ...
;     if (t < nt) { const int kt = t / tn, k0 = kt << 6, n0 = (t - kt * tn) << 6; v0 = *(const f32x4*)(src + (size_t)(k0 + lr) * N + n0 + lc); v1 = *(const f32x4*)(src + (size_t)(k0 + lr + 32) * N + n0 + lc); }
;     for (; t < nt; t += G) {
;         const int kt = t / tn, k0 = kt << 6, n0 = (t - kt * tn) << 6;
;         __syncthreads();
; #pragma unroll
;         for (int j = 0; j < 4; ++j) { tile[lr * 65 + lc + j] = v0[j]; tile[(lr + 32) * 65 + lc + j] = v1[j]; }
;         const int t2 = t + G;
;         if (t2 < nt) { const int kt2 = t2 / tn, k2 = kt2 << 6, n2 = (t2 - kt2 * tn) << 6; v0 = *(const f32x4*)(src + (size_t)(k2 + lr) * N + n2 + lc); v1 = *(const f32x4*)(src + (size_t)(k2 + lr + 32) * N + n2 + lc); }
; __device__ __forceinline__ void phase0(unsigned char* shm) {
;     ...
;     for (int l = 0; l < 2; ++l) {
;         bf16_t* W = (bf16_t*)(WSP() + (size_t)l * WL_BYTES);
;         tconv(IN(3) + (size_t)l * 1024 * 8960, W + oWin, 1024, 8960, IN(2) + l * 1024, tile, rot);
;         for (int k = 0; k < 4; ++k) tconv(IN(23) + (size_t)(l * 4 + k) * 512 * 1024, W + oWb + (size_t)k * 1024 * 512, 512, 1024, nullptr, tile, rot);
;         tconv(IN(24) + (size_t)l * 1024 * 1024, W + oWo, 1024, 1024, nullptr, tile, rot);
;         tconv(IN(26) + (size_t)l * 1024 * 5632, W + oWup, 1024, 5632, IN(25) + l * 1024, tile, rot);
;         tconv(IN(29) + (size_t)l * 2816 * 1024, W + oWd, 2816, 1024, nullptr, tile, rot);
;         tconv(IN(31) + (size_t)l * 256 * 1024, W + oWp, 256, 1024, nullptr, tile, rot);
;         tconv(IN(32) + (size_t)l * 1024 * 1024, W + oWg, 1024, 1024, IN(30) + l * 1024, tile, rot);
;         for (int g = 0; g < 4; ++g) tconv(IN(4) + (size_t)(l * 4 + g) * 128 * 128, W + oPw + (size_t)g * 16384, 128, 128, nullptr, tile, rot);
;         tconv(IN(8) + (size_t)l * 64 * 512, W + oW2, 64, 512, nullptr, tile, rot);
;         tconv(IN(10) + (size_t)l * 64 * 512, W + oA2, 64, 512, nullptr, tile, rot);
;         tconv(IN(11) + (size_t)l * 128 * 512, W + oG2, 128, 512, nullptr, tile, rot);
;     }
.Lp0p_m7:
	s_sub_u32 s4, s3, 4416
	s_mul_hi_u32 s5, s4, 0x10000000
	s_mul_i32 s8, s5, 16
	s_sub_u32 s8, s4, s8
	s_mul_i32 s9, s5, 0x40000
	s_lshl_b32 s10, s8, 8
	s_add_u32 s9, s9, s10
	s_mul_i32 s10, s2, 0xb00000
	s_add_u32 s9, s9, s10
	s_add_u32 s18, s48, s9
	s_addc_u32 s19, s49, 0
	s_mov_b32 s20, 0x1000
	s_mov_b64 s[22:23], s[38:39]
	s_branch .Lp0p_j
.Lp0p_m8:
	s_sub_u32 s4, s3, 5120
	s_mul_hi_u32 s5, s4, 0x10000000
	s_mul_i32 s8, s5, 16
	s_sub_u32 s8, s4, s8
	s_mul_i32 s9, s5, 0x40000
	s_lshl_b32 s10, s8, 8
	s_add_u32 s9, s9, s10
	s_mul_i32 s10, s2, 0x100000
	s_add_u32 s9, s9, s10
	s_add_u32 s18, s50, s9
	s_addc_u32 s19, s51, 0
	s_mov_b32 s20, 0x1000
	s_mov_b64 s[22:23], s[38:39]
	s_branch .Lp0p_j
.Lp0p_m9:
	s_sub_u32 s4, s3, 5184
	s_mul_hi_u32 s5, s4, 0x10000000
	s_mul_i32 s8, s5, 16
	s_sub_u32 s8, s4, s8
	s_mul_i32 s9, s5, 0x40000
	s_lshl_b32 s10, s8, 8
	s_add_u32 s9, s9, s10
	s_mul_i32 s10, s2, 0x400000
	s_add_u32 s9, s9, s10
	s_add_u32 s18, s52, s9
	s_addc_u32 s19, s53, 0
	s_mov_b32 s20, 0x1000
	s_lshl_b32 s9, s2, 12
	s_lshl_b32 s10, s5, 8
	s_add_u32 s9, s9, s10
	s_add_u32 s22, s54, s9
	s_addc_u32 s23, s55, 0
	s_branch .Lp0p_j
.Lp0p_m10:
	s_sub_u32 s4, s3, 5440
	s_mul_hi_u32 s5, s4, 0x80000000
	s_mul_i32 s8, s5, 2
	s_sub_u32 s8, s4, s8
	s_mul_i32 s9, s5, 0x8000
	s_lshl_b32 s10, s8, 8
	s_add_u32 s9, s9, s10
	s_mul_i32 s10, s2, 0x40000
	s_add_u32 s9, s9, s10
	s_add_u32 s18, s56, s9
	s_addc_u32 s19, s57, 0
	s_mov_b32 s20, 0x200
	s_mov_b64 s[22:23], s[38:39]
	s_branch .Lp0p_j
.Lp0p_m11:
	s_sub_u32 s4, s3, 5444
	s_mul_hi_u32 s5, s4, 0x80000000
	s_mul_i32 s8, s5, 2
	s_sub_u32 s8, s4, s8
	s_mul_i32 s9, s5, 0x8000
	s_lshl_b32 s10, s8, 8
	s_add_u32 s9, s9, s10
	s_mul_i32 s10, s2, 0x40000
	s_add_u32 s9, s9, s10
	s_add_u32 s9, s9, 0x10000
	s_add_u32 s18, s56, s9
	s_addc_u32 s19, s57, 0
	s_mov_b32 s20, 0x200
	s_mov_b64 s[22:23], s[38:39]
	s_branch .Lp0p_j
.Lp0p_m12:
	s_sub_u32 s4, s3, 5448
	s_mul_hi_u32 s5, s4, 0x80000000
	s_mul_i32 s8, s5, 2
	s_sub_u32 s8, s4, s8
	s_mul_i32 s9, s5, 0x8000
	s_lshl_b32 s10, s8, 8
	s_add_u32 s9, s9, s10
	s_mul_i32 s10, s2, 0x40000
	s_add_u32 s9, s9, s10
	s_add_u32 s9, s9, 0x20000
	s_add_u32 s18, s56, s9
	s_addc_u32 s19, s57, 0
	s_mov_b32 s20, 0x200
	s_mov_b64 s[22:23], s[38:39]
	s_branch .Lp0p_j
.Lp0p_m13:
	s_sub_u32 s4, s3, 5452
	s_mul_hi_u32 s5, s4, 0x80000000
	s_mul_i32 s8, s5, 2
	s_sub_u32 s8, s4, s8
	s_mul_i32 s9, s5, 0x8000
	s_lshl_b32 s10, s8, 8
	s_add_u32 s9, s9, s10
	s_mul_i32 s10, s2, 0x40000
	s_add_u32 s9, s9, s10
	s_add_u32 s9, s9, 0x30000
	s_add_u32 s18, s56, s9
	s_addc_u32 s19, s57, 0
	s_mov_b32 s20, 0x200
	s_mov_b64 s[22:23], s[38:39]
	s_branch .Lp0p_j
.Lp0p_m14:
	s_sub_u32 s4, s3, 5456
	s_mul_hi_u32 s5, s4, 0x20000000
	s_mul_i32 s8, s5, 8
	s_sub_u32 s8, s4, s8
	s_mul_i32 s9, s5, 0x20000
	s_lshl_b32 s10, s8, 8
	s_add_u32 s9, s9, s10
	s_mul_i32 s10, s2, 0x20000
	s_add_u32 s9, s9, s10
	s_add_u32 s18, s58, s9
	s_addc_u32 s19, s59, 0
	s_mov_b32 s20, 0x800
	s_mov_b64 s[22:23], s[38:39]
	s_branch .Lp0p_j
.Lp0p_m15:
	s_sub_u32 s4, s3, 5464
	s_mul_hi_u32 s5, s4, 0x20000000
	s_mul_i32 s8, s5, 8
	s_sub_u32 s8, s4, s8
	s_mul_i32 s9, s5, 0x20000
	s_lshl_b32 s10, s8, 8
	s_add_u32 s9, s9, s10
	s_mul_i32 s10, s2, 0x20000
	s_add_u32 s9, s9, s10
	s_add_u32 s18, s60, s9
	s_addc_u32 s19, s61, 0
	s_mov_b32 s20, 0x800
	s_mov_b64 s[22:23], s[38:39]
.Lp0p_j:
	v_mad_u32_u24 v4, v1, s20, v3
	v_mad_u32_u24 v5, v2, s20, v3
	s_add_u32 m0, s65, s67
	s_nop 0
	global_load_lds_dwordx4 v4, s[18:19]
	s_add_u32 m0, m0, 1040
	s_nop 0
	global_load_lds_dwordx4 v5, s[18:19]
	s_add_u32 m0, s65, 16640
	s_mov_b64 exec, 0xffff
	global_load_lds_dwordx4 v11, s[22:23]
	s_mov_b64 exec, -1
	s_add_u32 s65, s65, 16896
	s_cmp_ge_u32 s65, 118272
	s_cselect_b32 s8, 0, s65
	s_mov_b32 s65, s8
	s_add_u32 s68, s68, 1
	s_cmp_lt_u32 s68, 5
	s_cbranch_scc1 .Lp0_pro
.Lp0_loop:
	s_add_u32 s69, s64, 1280
	s_cmp_lt_u32 s69, 10976
	s_cselect_b32 s69, s69, s64
	s_cmp_ge_u32 s69, 5488
	s_cselect_b32 s2, 1, 0
	s_mul_i32 s3, s2, 5488
	s_sub_u32 s3, s69, s3
	s_cmp_lt_u32 s3, 2240
	s_cbranch_scc1 .Lp0l_m0
	s_cmp_lt_u32 s3, 2368
	s_cbranch_scc1 .Lp0l_m1
	s_cmp_lt_u32 s3, 2496
	s_cbranch_scc1 .Lp0l_m2
	s_cmp_lt_u32 s3, 2624
	s_cbranch_scc1 .Lp0l_m3
	s_cmp_lt_u32 s3, 2752
	s_cbranch_scc1 .Lp0l_m4
	s_cmp_lt_u32 s3, 3008
	s_cbranch_scc1 .Lp0l_m5
	s_cmp_lt_u32 s3, 4416
	s_cbranch_scc1 .Lp0l_m6
	s_cmp_lt_u32 s3, 5120
	s_cbranch_scc1 .Lp0l_m7
	s_cmp_lt_u32 s3, 5184
	s_cbranch_scc1 .Lp0l_m8
	s_cmp_lt_u32 s3, 5440
	s_cbranch_scc1 .Lp0l_m9
	s_cmp_lt_u32 s3, 5444
	s_cbranch_scc1 .Lp0l_m10
	s_cmp_lt_u32 s3, 5448
	s_cbranch_scc1 .Lp0l_m11
	s_cmp_lt_u32 s3, 5452
	s_cbranch_scc1 .Lp0l_m12
	s_cmp_lt_u32 s3, 5456
	s_cbranch_scc1 .Lp0l_m13
	s_cmp_lt_u32 s3, 5464
	s_cbranch_scc1 .Lp0l_m14
	s_cmp_lt_u32 s3, 5472
	s_cbranch_scc1 .Lp0l_m15
	s_sub_u32 s4, s3, 5472
	s_mul_hi_u32 s5, s4, 0x20000000
	s_mul_i32 s8, s5, 8
	s_sub_u32 s8, s4, s8
	s_mul_i32 s9, s5, 0x20000
	s_lshl_b32 s10, s8, 8
	s_add_u32 s9, s9, s10
	s_mul_i32 s10, s2, 0x40000
	s_add_u32 s9, s9, s10
	s_add_u32 s18, s62, s9
	s_addc_u32 s19, s63, 0
	s_mov_b32 s20, 0x800
	s_mov_b64 s[22:23], s[38:39]
	s_branch .Lp0l_j

; #define WSP() ((unsigned char*)karg_ptr<35 * 8>())
; __device__ __forceinline__ void tconv(const float* __restrict__ src, bf16_t* __restrict__ dst, int K, int N, const float* __restrict__ scale, float* tile, int& rot) {
;     ...
;     for (; t < nt; t += G) {
;         const int kt = t / tn, k0 = kt << 6, n0 = (t - kt * tn) << 6;
;         __syncthreads();
; #pragma unroll
;         for (int j = 0; j < 4; ++j) { tile[lr * 65 + lc + j] = v0[j]; tile[(lr + 32) * 65 + lc + j] = v1[j]; }
;         const int t2 = t + G;
;         if (t2 < nt) { const int kt2 = t2 / tn, k2 = kt2 << 6, n2 = (t2 - kt2 * tn) << 6; v0 = *(const f32x4*)(src + (size_t)(k2 + lr) * N + n2 + lc); v1 = *(const f32x4*)(src + (size_t)(k2 + lr + 32) * N + n2 + lc); }
;         __syncthreads();
; __device__ __forceinline__ void phase0(unsigned char* shm) {
;     ...
;     for (int l = 0; l < 2; ++l) {
;         bf16_t* W = (bf16_t*)(WSP() + (size_t)l * WL_BYTES);
;         tconv(IN(3) + (size_t)l * 1024 * 8960, W + oWin, 1024, 8960, IN(2) + l * 1024, tile, rot);
;         for (int k = 0; k < 4; ++k) tconv(IN(23) + (size_t)(l * 4 + k) * 512 * 1024, W + oWb + (size_t)k * 1024 * 512, 512, 1024, nullptr, tile, rot);
;         tconv(IN(24) + (size_t)l * 1024 * 1024, W + oWo, 1024, 1024, nullptr, tile, rot);
;         tconv(IN(26) + (size_t)l * 1024 * 5632, W + oWup, 1024, 5632, IN(25) + l * 1024, tile, rot);
;         tconv(IN(29) + (size_t)l * 2816 * 1024, W + oWd, 2816, 1024, nullptr, tile, rot);
;         tconv(IN(31) + (size_t)l * 256 * 1024, W + oWp, 256, 1024, nullptr, tile, rot);
;         tconv(IN(32) + (size_t)l * 1024 * 1024, W + oWg, 1024, 1024, IN(30) + l * 1024, tile, rot);
;         for (int g = 0; g < 4; ++g) tconv(IN(4) + (size_t)(l * 4 + g) * 128 * 128, W + oPw + (size_t)g * 16384, 128, 128, nullptr, tile, rot);
;         tconv(IN(8) + (size_t)l * 64 * 512, W + oW2, 64, 512, nullptr, tile, rot);
;         tconv(IN(10) + (size_t)l * 64 * 512, W + oA2, 64, 512, nullptr, tile, rot);
;         tconv(IN(11) + (size_t)l * 128 * 512, W + oG2, 128, 512, nullptr, tile, rot);
;     }
.Lp0l_j:
	v_mad_u32_u24 v4, v1, s20, v3
	v_mad_u32_u24 v5, v2, s20, v3
	s_add_u32 m0, s65, s67
	s_nop 0
	global_load_lds_dwordx4 v4, s[18:19]
	s_add_u32 m0, m0, 1040
	s_nop 0
	global_load_lds_dwordx4 v5, s[18:19]
	s_add_u32 m0, s65, 16640
	s_mov_b64 exec, 0xffff
	global_load_lds_dwordx4 v11, s[22:23]
	s_mov_b64 exec, -1
	s_add_u32 s65, s65, 16896
	s_cmp_ge_u32 s65, 118272
	s_cselect_b32 s8, 0, s65
	s_mov_b32 s65, s8
	s_waitcnt vmcnt(15)
	s_barrier
	s_cmp_ge_u32 s64, 5488
	s_cselect_b32 s2, 1, 0
	s_mul_i32 s3, s2, 5488
	s_sub_u32 s3, s64, s3
	s_cmp_lt_u32 s3, 2240
	s_cbranch_scc1 .Lp0s_m0
	s_cmp_lt_u32 s3, 2368
	s_cbranch_scc1 .Lp0s_m1
	s_cmp_lt_u32 s3, 2496
	s_cbranch_scc1 .Lp0s_m2
	s_cmp_lt_u32 s3, 2624
	s_cbranch_scc1 .Lp0s_m3
	s_cmp_lt_u32 s3, 2752
	s_cbranch_scc1 .Lp0s_m4
	s_cmp_lt_u32 s3, 3008
	s_cbranch_scc1 .Lp0s_m5
	s_cmp_lt_u32 s3, 4416
	s_cbranch_scc1 .Lp0s_m6
	s_cmp_lt_u32 s3, 5120
	s_cbranch_scc1 .Lp0s_m7
	s_cmp_lt_u32 s3, 5184
	s_cbranch_scc1 .Lp0s_m8
	s_cmp_lt_u32 s3, 5440
	s_cbranch_scc1 .Lp0s_m9
	s_cmp_lt_u32 s3, 5444
	s_cbranch_scc1 .Lp0s_m10
	s_cmp_lt_u32 s3, 5448
	s_cbranch_scc1 .Lp0s_m11
	s_cmp_lt_u32 s3, 5452
	s_cbranch_scc1 .Lp0s_m12
	s_cmp_lt_u32 s3, 5456
	s_cbranch_scc1 .Lp0s_m13
	s_cmp_lt_u32 s3, 5464
	s_cbranch_scc1 .Lp0s_m14
	s_cmp_lt_u32 s3, 5472
	s_cbranch_scc1 .Lp0s_m15
	s_sub_u32 s4, s3, 5472
	s_mul_hi_u32 s5, s4, 0x20000000
	s_mul_i32 s8, s5, 8
	s_sub_u32 s8, s4, s8
	s_mul_i32 s9, s8, 0x4000
	s_lshl_b32 s10, s5, 7
	s_add_u32 s9, s9, s10
	s_mul_i32 s10, s2, 0x2b00000
	s_add_u32 s9, s9, s10
	s_add_u32 s9, s9, 0x2ac0000
	s_add_u32 s24, s14, s9
	s_addc_u32 s25, s15, 0
	s_mov_b32 s26, 0x100
	s_mov_b32 s27, 0
	s_branch .Lp0s_j
.Lp0s_m0:
	s_sub_u32 s4, s3, 0
	s_mul_hi_u32 s5, s4, 0x1d41d42
	s_mul_i32 s8, s5, 140
	s_sub_u32 s8, s4, s8
	s_mul_i32 s9, s8, 0x20000
	s_lshl_b32 s10, s5, 7
	s_add_u32 s9, s9, s10
	s_mul_i32 s10, s2, 0x2b00000
	s_add_u32 s9, s9, s10
	s_add_u32 s9, s9, 0x0
	s_add_u32 s24, s14, s9
	s_addc_u32 s25, s15, 0
	s_mov_b32 s26, 0x800
	s_mov_b32 s27, 1
	s_branch .Lp0s_j
.Lp0s_m1:
	s_sub_u32 s4, s3, 2240
	s_mul_hi_u32 s5, s4, 0x10000000
	s_mul_i32 s8, s5, 16
	s_sub_u32 s8, s4, s8
	s_mul_i32 s9, s8, 0x10000
	s_lshl_b32 s10, s5, 7
	s_add_u32 s9, s9, s10
	s_mul_i32 s10, s2, 0x2b00000
	s_add_u32 s9, s9, s10
	s_add_u32 s9, s9, 0x1180000
	s_add_u32 s24, s14, s9
	s_addc_u32 s25, s15, 0
	s_mov_b32 s26, 0x400
	s_mov_b32 s27, 0
	s_branch .Lp0s_j
.Lp0s_m2:
	s_sub_u32 s4, s3, 2368
	s_mul_hi_u32 s5, s4, 0x10000000
	s_mul_i32 s8, s5, 16
	s_sub_u32 s8, s4, s8
	s_mul_i32 s9, s8, 0x10000
	s_lshl_b32 s10, s5, 7
	s_add_u32 s9, s9, s10
	s_mul_i32 s10, s2, 0x2b00000
	s_add_u32 s9, s9, s10
	s_add_u32 s9, s9, 0x1280000
	s_add_u32 s24, s14, s9
	s_addc_u32 s25, s15, 0
	s_mov_b32 s26, 0x400
	s_mov_b32 s27, 0
	s_branch .Lp0s_j
.Lp0s_m3:
	s_sub_u32 s4, s3, 2496
	s_mul_hi_u32 s5, s4, 0x10000000
	s_mul_i32 s8, s5, 16
	s_sub_u32 s8, s4, s8
	s_mul_i32 s9, s8, 0x10000
	s_lshl_b32 s10, s5, 7
	s_add_u32 s9, s9, s10
	s_mul_i32 s10, s2, 0x2b00000
	s_add_u32 s9, s9, s10
	s_add_u32 s9, s9, 0x1380000
	s_add_u32 s24, s14, s9
	s_addc_u32 s25, s15, 0
	s_mov_b32 s26, 0x400
	s_mov_b32 s27, 0
	s_branch .Lp0s_j
.Lp0s_m4:
	s_sub_u32 s4, s3, 2624
	s_mul_hi_u32 s5, s4, 0x10000000
	s_mul_i32 s8, s5, 16
	s_sub_u32 s8, s4, s8
	s_mul_i32 s9, s8, 0x10000
	s_lshl_b32 s10, s5, 7
	s_add_u32 s9, s9, s10
	s_mul_i32 s10, s2, 0x2b00000
	s_add_u32 s9, s9, s10
	s_add_u32 s9, s9, 0x1480000
	s_add_u32 s24, s14, s9
	s_addc_u32 s25, s15, 0
	s_mov_b32 s26, 0x400
	s_mov_b32 s27, 0
	s_branch .Lp0s_j
.Lp0s_m5:
	s_sub_u32 s4, s3, 2752
	s_mul_hi_u32 s5, s4, 0x10000000
	s_mul_i32 s8, s5, 16
	s_sub_u32 s8, s4, s8
	s_mul_i32 s9, s8, 0x20000
	s_lshl_b32 s10, s5, 7
	s_add_u32 s9, s9, s10
	s_mul_i32 s10, s2, 0x2b00000
	s_add_u32 s9, s9, s10
	s_add_u32 s9, s9, 0x1580000
	s_add_u32 s24, s14, s9
	s_addc_u32 s25, s15, 0
	s_mov_b32 s26, 0x800
	s_mov_b32 s27, 0
	s_branch .Lp0s_j
.Lp0s_m6:
	s_sub_u32 s4, s3, 3008
	s_mul_hi_u32 s5, s4, 0x2e8ba2f
	s_mul_i32 s8, s5, 88
	s_sub_u32 s8, s4, s8
	s_mul_i32 s9, s8, 0x20000
	s_lshl_b32 s10, s5, 7
	s_add_u32 s9, s9, s10
	s_mul_i32 s10, s2, 0x2b00000
	s_add_u32 s9, s9, s10
	s_add_u32 s9, s9, 0x1780000
	s_add_u32 s24, s14, s9
	s_addc_u32 s25, s15, 0
	s_mov_b32 s26, 0x800
	s_mov_b32 s27, 1
	s_branch .Lp0s_j
; __device__ __forceinline__ u32x4 pack8(const f32x4& v0, const f32x4& v1) { u32x4 w; w.x = cvt_pk_bf16(v0[0], v0[1]); w.y = cvt_pk_bf16(v0[2], v0[3]); w.z = cvt_pk_bf16(v1[0], v1[1]); w.w = cvt_pk_bf16(v1[2], v1[3]); return w; }
; __device__ __forceinline__ void tconv(const float* __restrict__ src, bf16_t* __restrict__ dst, int K, int N, const float* __restrict__ scale, float* tile, int& rot) {
;     ...
;         __syncthreads();
;         f32x4 a, bb;
; #pragma unroll
;         for (int j = 0; j < 4; ++j) { a[j] = tile[(sk + j) * 65 + sn]; bb[j] = tile[(sk + 4 + j) * 65 + sn]; }
;         if (scale) { a *= *(const f32x4*)(scale + k0 + sk); bb *= *(const f32x4*)(scale + k0 + sk + 4); }
;         *(u32x4*)(dst + (size_t)(n0 + sn) * K + k0 + sk) = pack8(a, bb);
;     }
.Lp0s_m7:
	s_sub_u32 s4, s3, 4416
	s_mul_hi_u32 s5, s4, 0x10000000
	s_mul_i32 s8, s5, 16
	s_sub_u32 s8, s4, s8
	s_mul_i32 s9, s8, 0x58000
	s_lshl_b32 s10, s5, 7
	s_add_u32 s9, s9, s10
	s_mul_i32 s10, s2, 0x2b00000
	s_add_u32 s9, s9, s10
	s_add_u32 s9, s9, 0x2280000
	s_add_u32 s24, s14, s9
	s_addc_u32 s25, s15, 0
	s_mov_b32 s26, 0x1600
	s_mov_b32 s27, 0
	s_branch .Lp0s_j
.Lp0s_m8:
	s_sub_u32 s4, s3, 5120
	s_mul_hi_u32 s5, s4, 0x10000000
	s_mul_i32 s8, s5, 16
	s_sub_u32 s8, s4, s8
	s_mul_i32 s9, s8, 0x8000
	s_lshl_b32 s10, s5, 7
	s_add_u32 s9, s9, s10
	s_mul_i32 s10, s2, 0x2b00000
	s_add_u32 s9, s9, s10
	s_add_u32 s9, s9, 0x2800000
	s_add_u32 s24, s14, s9
	s_addc_u32 s25, s15, 0
	s_mov_b32 s26, 0x200
	s_mov_b32 s27, 0
	s_branch .Lp0s_j
.Lp0s_m9:
	s_sub_u32 s4, s3, 5184
	s_mul_hi_u32 s5, s4, 0x10000000
	s_mul_i32 s8, s5, 16
	s_sub_u32 s8, s4, s8
	s_mul_i32 s9, s8, 0x20000
	s_lshl_b32 s10, s5, 7
	s_add_u32 s9, s9, s10
	s_mul_i32 s10, s2, 0x2b00000
	s_add_u32 s9, s9, s10
	s_add_u32 s9, s9, 0x2880000
	s_add_u32 s24, s14, s9
	s_addc_u32 s25, s15, 0
	s_mov_b32 s26, 0x800
	s_mov_b32 s27, 1
	s_branch .Lp0s_j
.Lp0s_m10:
	s_sub_u32 s4, s3, 5440
	s_mul_hi_u32 s5, s4, 0x80000000
	s_mul_i32 s8, s5, 2
	s_sub_u32 s8, s4, s8
	s_mul_i32 s9, s8, 0x4000
	s_lshl_b32 s10, s5, 7
	s_add_u32 s9, s9, s10
	s_mul_i32 s10, s2, 0x2b00000
	s_add_u32 s9, s9, s10
	s_add_u32 s9, s9, 0x2a80000
	s_add_u32 s24, s14, s9
	s_addc_u32 s25, s15, 0
	s_mov_b32 s26, 0x100
	s_mov_b32 s27, 0
	s_branch .Lp0s_j
.Lp0s_m11:
	s_sub_u32 s4, s3, 5444
	s_mul_hi_u32 s5, s4, 0x80000000
	s_mul_i32 s8, s5, 2
	s_sub_u32 s8, s4, s8
	s_mul_i32 s9, s8, 0x4000
	s_lshl_b32 s10, s5, 7
	s_add_u32 s9, s9, s10
	s_mul_i32 s10, s2, 0x2b00000
	s_add_u32 s9, s9, s10
	s_add_u32 s9, s9, 0x2a88000
	s_add_u32 s24, s14, s9
	s_addc_u32 s25, s15, 0
	s_mov_b32 s26, 0x100
	s_mov_b32 s27, 0
	s_branch .Lp0s_j
.Lp0s_m12:
	s_sub_u32 s4, s3, 5448
	s_mul_hi_u32 s5, s4, 0x80000000
	s_mul_i32 s8, s5, 2
	s_sub_u32 s8, s4, s8
	s_mul_i32 s9, s8, 0x4000
	s_lshl_b32 s10, s5, 7
	s_add_u32 s9, s9, s10
	s_mul_i32 s10, s2, 0x2b00000
	s_add_u32 s9, s9, s10
	s_add_u32 s9, s9, 0x2a90000
	s_add_u32 s24, s14, s9
	s_addc_u32 s25, s15, 0
	s_mov_b32 s26, 0x100
	s_mov_b32 s27, 0
	s_branch .Lp0s_j
.Lp0s_m13:
	s_sub_u32 s4, s3, 5452
	s_mul_hi_u32 s5, s4, 0x80000000
	s_mul_i32 s8, s5, 2
	s_sub_u32 s8, s4, s8
	s_mul_i32 s9, s8, 0x4000
	s_lshl_b32 s10, s5, 7
	s_add_u32 s9, s9, s10
	s_mul_i32 s10, s2, 0x2b00000
	s_add_u32 s9, s9, s10
	s_add_u32 s9, s9, 0x2a98000
	s_add_u32 s24, s14, s9
	s_addc_u32 s25, s15, 0
	s_mov_b32 s26, 0x100
	s_mov_b32 s27, 0
	s_branch .Lp0s_j
.Lp0s_m14:
	s_sub_u32 s4, s3, 5456
	s_mul_hi_u32 s5, s4, 0x20000000
	s_mul_i32 s8, s5, 8
	s_sub_u32 s8, s4, s8
	s_mul_i32 s9, s8, 0x2000
	s_lshl_b32 s10, s5, 7
	s_add_u32 s9, s9, s10
	s_mul_i32 s10, s2, 0x2b00000
	s_add_u32 s9, s9, s10
	s_add_u32 s9, s9, 0x2aa0000
	s_add_u32 s24, s14, s9
	s_addc_u32 s25, s15, 0
	s_mov_b32 s26, 0x80
	s_mov_b32 s27, 0
	s_branch .Lp0s_j
.Lp0s_m15:
	s_sub_u32 s4, s3, 5464
	s_mul_hi_u32 s5, s4, 0x20000000
	s_mul_i32 s8, s5, 8
	s_sub_u32 s8, s4, s8
	s_mul_i32 s9, s8, 0x2000
	s_lshl_b32 s10, s5, 7
	s_add_u32 s9, s9, s10
	s_mul_i32 s10, s2, 0x2b00000
	s_add_u32 s9, s9, s10
	s_add_u32 s9, s9, 0x2ab0000
	s_add_u32 s24, s14, s9
	s_addc_u32 s25, s15, 0
	s_mov_b32 s26, 0x80
	s_mov_b32 s27, 0
.Lp0s_j:
	v_add_u32_e32 v32, s66, v9
	ds_read_b32 v12, v32
	ds_read_b32 v13, v32 offset:256
	ds_read_b32 v14, v32 offset:512
	ds_read_b32 v15, v32 offset:768
	ds_read_b32 v16, v32 offset:1040
	ds_read_b32 v17, v32 offset:1296
	ds_read_b32 v18, v32 offset:1552
	ds_read_b32 v19, v32 offset:1808
	v_add_u32_e32 v33, s66, v10
	ds_read_b128 v[20:23], v33 offset:16640
	ds_read_b128 v[24:27], v33 offset:16656
	v_mad_u32_u24 v8, v6, s26, v7
	s_cmp_eq_u32 s27, 0
	s_waitcnt lgkmcnt(0)
	s_cbranch_scc1 .Lp0_nosc
	v_pk_mul_f32 v[12:13], v[12:13], v[20:21]
	v_pk_mul_f32 v[14:15], v[14:15], v[22:23]
	v_pk_mul_f32 v[16:17], v[16:17], v[24:25]
	v_pk_mul_f32 v[18:19], v[18:19], v[26:27]
.Lp0_nosc:
	v_cvt_pk_bf16_f32 v28, v12, v13
	v_cvt_pk_bf16_f32 v29, v14, v15
	v_cvt_pk_bf16_f32 v30, v16, v17
	v_cvt_pk_bf16_f32 v31, v18, v19
	global_store_dwordx4 v8, v[28:31], s[24:25]
	s_add_u32 s66, s66, 16896
	s_cmp_ge_u32 s66, 118272
	s_cselect_b32 s66, 0, s66
	s_add_u32 s64, s64, 256
	s_cmp_lt_u32 s64, 10976
	s_cbranch_scc1 .Lp0_loop
	s_waitcnt vmcnt(0)
